# RESID epilogue: residual row loads hoisted 13 items ahead with counted waits
# baseline (speedup 1.0000x reference)
; #define PG8_STAGE(bufoff, gbase, voff) do { _Pragma("unroll") for (int _i = 0; _i < 2; ++_i) \
;         __builtin_amdgcn_global_load_lds((const unsigned*)((const char*)(gbase) + (voff)[_i]), (PG8_LAS unsigned*)(lds + (bufoff) + ldsw + _i * 8192), 16, 0, 0); } while (0)
; #define PG8_LDA(dst, b, h) do { _Pragma("unroll") for (int m = 0; m < 4; ++m) _Pragma("unroll") for (int k = 0; k < 2; ++k) dst[m][k] = *(const PG8_LAS bf16x8*)(lds + PG8_SA(b, h) + aoff + m * 2048 + k * 1024); } while (0)
; #define PG8_LDB(dst, b, h) do { _Pragma("unroll") for (int n = 0; n < 2; ++n) _Pragma("unroll") for (int k = 0; k < 2; ++k) dst[n][k] = *(const PG8_LAS bf16x8*)(lds + PG8_SB(b, h) + boff + n * 2048 + k * 1024); } while (0)
; #define PG8_MMA(ai, bj, At, Bt) do { __builtin_amdgcn_s_setprio(1); _Pragma("unroll") for (int m = 0; m < 4; ++m) _Pragma("unroll") for (int n = 0; n < 2; ++n) _Pragma("unroll") for (int k = 0; k < 2; ++k) \
;         acc[ai][bj][m][n] = __builtin_amdgcn_mfma_f32_16x16x32_bf16(Bt[n][k], At[m][k], acc[ai][bj][m][n], 0, 0, 0); __builtin_amdgcn_s_setprio(0); } while (0)
; #define PG8_WAIT_V(n) asm volatile("s_waitcnt vmcnt(" #n ")" ::: "memory")
; #define PG8_WAIT_L(n) asm volatile("s_waitcnt lgkmcnt(" #n ")" ::: "memory")
; #define PG8_BAR __builtin_amdgcn_s_barrier()
; #define PG8_SCHED __builtin_amdgcn_sched_barrier(0)
; template <class Epi, class Sched, bool ALIGN_EPI = false, bool SP2 = false>
; __device__ __forceinline__ void gemm_phase(PG8_LAS unsigned char* lds, const Gemm g, const Sched& S, const Epi& E, int wave_in) {
;     ...
;             PG8_LDB(B0, 0, 0); PG8_LDB(B1, 0, 1); PG8_SCHED; PG8_LDA(At, 0, 0); PG8_STAGE(PG8_SA(1, 1), a1 + hstepA, voffA);
;             PG8_WAIT_V(8); PG8_WAIT_L(0); PG8_BAR; PG8_MMA(0, 0, At, B0); PG8_MMA(0, 1, At, B1); PG8_BAR; PG8_SCHED;
;             PG8_LDA(At, 0, 1); PG8_STAGE(PG8_SB(0, 0), b2, voffB); PG8_STAGE(PG8_SB(0, 1), b2 + hstep, voffB); PG8_STAGE(PG8_SA(0, 0), a2, voffA);
;             PG8_WAIT_V(8); PG8_WAIT_L(0); PG8_BAR; PG8_MMA(1, 0, At, B0); PG8_MMA(1, 1, At, B1); PG8_BAR; PG8_SCHED;
.Lmg_nohook:
	s_add_i32 s43, s6, 2
	s_add_u32 s44, s4, 0x80
	s_addc_u32 s7, s5, 0
	s_add_i32 s46, 0, 0x10000
	s_cmp_eq_u32 s37, s6
	s_cselect_b32 s7, s21, s7
	s_cselect_b32 s6, s20, s44
	s_cselect_b32 s45, s23, s25
	s_cselect_b32 s44, s22, s24
	s_add_i32 s47, 0, 0x14000
	v_add_u32_e32 v168, s46, v149
	v_add_u32_e32 v184, s47, v149
	ds_read_b128 v[140:143], v168
	ds_read_b128 v[144:147], v168 offset:1024
	ds_read_b128 v[154:157], v168 offset:2048
	ds_read_b128 v[168:171], v168 offset:3072
	ds_read_b128 v[172:175], v184
	ds_read_b128 v[176:179], v184 offset:1024
	ds_read_b128 v[180:183], v184 offset:2048
	ds_read_b128 v[184:187], v184 offset:3072
	v_lshl_add_u64 v[192:193], s[4:5], 0, v[136:137]
	s_add_i32 m0, s28, 0xc000
	ds_read_b128 v[188:191], v153
	ds_read_b128 v[212:215], v153 offset:1024
	ds_read_b128 v[216:219], v153 offset:2048
	ds_read_b128 v[220:223], v153 offset:3072
	ds_read_b128 v[224:227], v153 offset:4096
	ds_read_b128 v[228:231], v153 offset:5120
	ds_read_b128 v[232:235], v153 offset:6144
	ds_read_b128 v[236:239], v153 offset:7168
	global_load_lds_dwordx4 v[192:193], off
	v_lshl_add_u64 v[192:193], s[4:5], 0, v[138:139]
	s_add_i32 m0, s28, 0xe000
	s_nop 0
	global_load_lds_dwordx4 v[192:193], off
	s_waitcnt vmcnt(8)
	s_waitcnt lgkmcnt(0)
	s_barrier
	s_waitcnt lgkmcnt(0)
	v_mfma_f32_16x16x32_bf16 v[126:129], v[140:143], v[188:191], v[126:129]
	v_mfma_f32_16x16x32_bf16 v[122:125], v[154:157], v[188:191], v[122:125]
	v_mfma_f32_16x16x32_bf16 v[110:113], v[140:143], v[216:219], v[110:113]
	v_mfma_f32_16x16x32_bf16 v[106:109], v[154:157], v[216:219], v[106:109]
	v_mfma_f32_16x16x32_bf16 v[94:97], v[140:143], v[224:227], v[94:97]
	v_mfma_f32_16x16x32_bf16 v[90:93], v[154:157], v[224:227], v[90:93]
	v_mfma_f32_16x16x32_bf16 v[78:81], v[140:143], v[232:235], v[78:81]
	v_mfma_f32_16x16x32_bf16 v[74:77], v[154:157], v[232:235], v[74:77]
	v_mfma_f32_16x16x32_bf16 v[126:129], v[144:147], v[212:215], v[126:129]
	v_mfma_f32_16x16x32_bf16 v[122:125], v[168:171], v[212:215], v[122:125]
	v_mfma_f32_16x16x32_bf16 v[110:113], v[144:147], v[220:223], v[110:113]
	v_mfma_f32_16x16x32_bf16 v[106:109], v[168:171], v[220:223], v[106:109]
	v_mfma_f32_16x16x32_bf16 v[94:97], v[144:147], v[228:231], v[94:97]
	v_mfma_f32_16x16x32_bf16 v[90:93], v[168:171], v[228:231], v[90:93]
	v_mfma_f32_16x16x32_bf16 v[78:81], v[144:147], v[236:239], v[78:81]
	v_mfma_f32_16x16x32_bf16 v[74:77], v[168:171], v[236:239], v[74:77]
	v_mfma_f32_16x16x32_bf16 v[118:121], v[172:175], v[188:191], v[118:121]
	v_mfma_f32_16x16x32_bf16 v[114:117], v[180:183], v[188:191], v[114:117]
	v_mfma_f32_16x16x32_bf16 v[102:105], v[172:175], v[216:219], v[102:105]
	v_mfma_f32_16x16x32_bf16 v[98:101], v[180:183], v[216:219], v[98:101]
	v_mfma_f32_16x16x32_bf16 v[86:89], v[172:175], v[224:227], v[86:89]
	v_mfma_f32_16x16x32_bf16 v[82:85], v[180:183], v[224:227], v[82:85]
	v_mfma_f32_16x16x32_bf16 v[70:73], v[172:175], v[232:235], v[70:73]
	v_mfma_f32_16x16x32_bf16 v[66:69], v[180:183], v[232:235], v[66:69]
	v_mfma_f32_16x16x32_bf16 v[118:121], v[176:179], v[212:215], v[118:121]
	v_mfma_f32_16x16x32_bf16 v[114:117], v[184:187], v[212:215], v[114:117]
	v_mfma_f32_16x16x32_bf16 v[102:105], v[176:179], v[220:223], v[102:105]
	v_mfma_f32_16x16x32_bf16 v[98:101], v[184:187], v[220:223], v[98:101]
	v_mfma_f32_16x16x32_bf16 v[86:89], v[176:179], v[228:231], v[86:89]
	v_mfma_f32_16x16x32_bf16 v[82:85], v[184:187], v[228:231], v[82:85]
	v_mfma_f32_16x16x32_bf16 v[70:73], v[176:179], v[236:239], v[70:73]
	v_mfma_f32_16x16x32_bf16 v[66:69], v[184:187], v[236:239], v[66:69]
	s_barrier
	s_add_i32 s46, s46, s27
	v_lshl_add_u64 v[192:193], s[44:45], 0, v[0:1]
	s_mov_b32 m0, s46
	ds_read_b128 v[188:191], v153 offset:16384
	ds_read_b128 v[212:215], v153 offset:17408
	ds_read_b128 v[216:219], v153 offset:18432
	ds_read_b128 v[220:223], v153 offset:19456
	ds_read_b128 v[224:227], v153 offset:20480
	ds_read_b128 v[228:231], v153 offset:21504
	ds_read_b128 v[232:235], v153 offset:22528
	ds_read_b128 v[236:239], v153 offset:23552
	global_load_lds_dwordx4 v[192:193], off
	s_add_i32 m0, s46, 0x2000
	v_lshl_add_u64 v[200:201], s[44:45], 0, v[130:131]
	s_add_u32 s44, s44, s78
	s_addc_u32 s45, s45, 0
	s_add_i32 s46, s47, s27
	global_load_lds_dwordx4 v[200:201], off
	v_lshl_add_u64 v[240:241], s[44:45], 0, v[0:1]
	s_mov_b32 m0, s46
	v_lshl_add_u64 v[242:243], s[44:45], 0, v[130:131]
	global_load_lds_dwordx4 v[240:241], off
	s_add_i32 m0, s46, 0x2000
	v_lshl_add_u64 v[244:245], s[6:7], 0, v[134:135]
	global_load_lds_dwordx4 v[242:243], off
	s_mov_b32 m0, s28
	v_lshl_add_u64 v[246:247], s[6:7], 0, v[132:133]
	global_load_lds_dwordx4 v[244:245], off
	s_mov_b32 m0, s29
	s_nop 0
	global_load_lds_dwordx4 v[246:247], off
	s_waitcnt vmcnt(8)
	s_waitcnt lgkmcnt(0)
	s_barrier
; #define PG8_STAGE(bufoff, gbase, voff) do { _Pragma("unroll") for (int _i = 0; _i < 2; ++_i) \
;         __builtin_amdgcn_global_load_lds((const unsigned*)((const char*)(gbase) + (voff)[_i]), (PG8_LAS unsigned*)(lds + (bufoff) + ldsw + _i * 8192), 16, 0, 0); } while (0)
; #define PG8_LDA(dst, b, h) do { _Pragma("unroll") for (int m = 0; m < 4; ++m) _Pragma("unroll") for (int k = 0; k < 2; ++k) dst[m][k] = *(const PG8_LAS bf16x8*)(lds + PG8_SA(b, h) + aoff + m * 2048 + k * 1024); } while (0)
; #define PG8_LDB(dst, b, h) do { _Pragma("unroll") for (int n = 0; n < 2; ++n) _Pragma("unroll") for (int k = 0; k < 2; ++k) dst[n][k] = *(const PG8_LAS bf16x8*)(lds + PG8_SB(b, h) + boff + n * 2048 + k * 1024); } while (0)
; #define PG8_MMA(ai, bj, At, Bt) do { __builtin_amdgcn_s_setprio(1); _Pragma("unroll") for (int m = 0; m < 4; ++m) _Pragma("unroll") for (int n = 0; n < 2; ++n) _Pragma("unroll") for (int k = 0; k < 2; ++k) \
;         acc[ai][bj][m][n] = __builtin_amdgcn_mfma_f32_16x16x32_bf16(Bt[n][k], At[m][k], acc[ai][bj][m][n], 0, 0, 0); __builtin_amdgcn_s_setprio(0); } while (0)
; #define PG8_WAIT_V(n) asm volatile("s_waitcnt vmcnt(" #n ")" ::: "memory")
; #define PG8_WAIT_L(n) asm volatile("s_waitcnt lgkmcnt(" #n ")" ::: "memory")
; #define PG8_BAR __builtin_amdgcn_s_barrier()
; #define PG8_SCHED __builtin_amdgcn_sched_barrier(0)
; template <class Epi, class Sched, bool ALIGN_EPI = false, bool SP2 = false>
; __device__ __forceinline__ void gemm_phase(PG8_LAS unsigned char* lds, const Gemm g, const Sched& S, const Epi& E, int wave_in) {
;     ...
;             PG8_WAIT_V(8); PG8_WAIT_L(0); PG8_BAR; PG8_MMA(1, 0, At, B0); PG8_MMA(1, 1, At, B1); PG8_BAR; PG8_SCHED;
;             PG8_LDB(B0, 1, 0); PG8_LDB(B1, 1, 1); PG8_SCHED; PG8_LDA(At, 1, 0); PG8_STAGE(PG8_SA(0, 1), a2 + hstepA, voffA);
;             PG8_WAIT_V(8); PG8_WAIT_L(0); PG8_BAR; PG8_MMA(0, 0, At, B0); PG8_MMA(0, 1, At, B1); PG8_BAR; PG8_SCHED;
;             PG8_LDA(At, 1, 1); PG8_STAGE(PG8_SB(1, 0), b3, voffB); PG8_STAGE(PG8_SB(1, 1), b3 + hstep, voffB); PG8_STAGE(PG8_SA(1, 0), a3, voffA);
	s_waitcnt lgkmcnt(0)
	v_mfma_f32_16x16x32_bf16 v[62:65], v[140:143], v[188:191], v[62:65]
	v_mfma_f32_16x16x32_bf16 v[58:61], v[154:157], v[188:191], v[58:61]
	v_mfma_f32_16x16x32_bf16 v[46:49], v[140:143], v[216:219], v[46:49]
	v_mfma_f32_16x16x32_bf16 v[42:45], v[154:157], v[216:219], v[42:45]
	v_mfma_f32_16x16x32_bf16 v[30:33], v[140:143], v[224:227], v[30:33]
	v_mfma_f32_16x16x32_bf16 v[26:29], v[154:157], v[224:227], v[26:29]
	v_mfma_f32_16x16x32_bf16 v[14:17], v[140:143], v[232:235], v[14:17]
	v_mfma_f32_16x16x32_bf16 v[10:13], v[154:157], v[232:235], v[10:13]
	v_mfma_f32_16x16x32_bf16 v[62:65], v[144:147], v[212:215], v[62:65]
	v_mfma_f32_16x16x32_bf16 v[58:61], v[168:171], v[212:215], v[58:61]
	v_mfma_f32_16x16x32_bf16 v[46:49], v[144:147], v[220:223], v[46:49]
	v_mfma_f32_16x16x32_bf16 v[42:45], v[168:171], v[220:223], v[42:45]
	v_mfma_f32_16x16x32_bf16 v[30:33], v[144:147], v[228:231], v[30:33]
	v_mfma_f32_16x16x32_bf16 v[26:29], v[168:171], v[228:231], v[26:29]
	v_mfma_f32_16x16x32_bf16 v[14:17], v[144:147], v[236:239], v[14:17]
	v_mfma_f32_16x16x32_bf16 v[10:13], v[168:171], v[236:239], v[10:13]
	v_mfma_f32_16x16x32_bf16 v[54:57], v[172:175], v[188:191], v[54:57]
	v_mfma_f32_16x16x32_bf16 v[50:53], v[180:183], v[188:191], v[50:53]
	v_mfma_f32_16x16x32_bf16 v[38:41], v[172:175], v[216:219], v[38:41]
	v_mfma_f32_16x16x32_bf16 v[34:37], v[180:183], v[216:219], v[34:37]
	v_mfma_f32_16x16x32_bf16 v[22:25], v[172:175], v[224:227], v[22:25]
	v_mfma_f32_16x16x32_bf16 v[18:21], v[180:183], v[224:227], v[18:21]
	v_mfma_f32_16x16x32_bf16 v[6:9], v[172:175], v[232:235], v[6:9]
	v_mfma_f32_16x16x32_bf16 v[2:5], v[180:183], v[232:235], v[2:5]
	v_mfma_f32_16x16x32_bf16 v[54:57], v[176:179], v[212:215], v[54:57]
	v_mfma_f32_16x16x32_bf16 v[50:53], v[184:187], v[212:215], v[50:53]
	v_mfma_f32_16x16x32_bf16 v[38:41], v[176:179], v[220:223], v[38:41]
	v_mfma_f32_16x16x32_bf16 v[34:37], v[184:187], v[220:223], v[34:37]
	v_mfma_f32_16x16x32_bf16 v[22:25], v[176:179], v[228:231], v[22:25]
	v_mfma_f32_16x16x32_bf16 v[18:21], v[184:187], v[228:231], v[18:21]
	v_mfma_f32_16x16x32_bf16 v[6:9], v[176:179], v[236:239], v[6:9]
	v_mfma_f32_16x16x32_bf16 v[2:5], v[184:187], v[236:239], v[2:5]
	s_barrier
	s_add_i32 s44, 0, 0x18000
	s_add_i32 s45, 0, 0x1c000
	v_add_u32_e32 v168, s44, v149
	v_add_u32_e32 v184, s45, v149
	ds_read_b128 v[140:143], v168
	ds_read_b128 v[144:147], v168 offset:1024
	ds_read_b128 v[154:157], v168 offset:2048
	ds_read_b128 v[168:171], v168 offset:3072
	ds_read_b128 v[172:175], v184
	ds_read_b128 v[176:179], v184 offset:1024
	ds_read_b128 v[180:183], v184 offset:2048
	ds_read_b128 v[184:187], v184 offset:3072
	s_add_u32 s6, s6, s78
	s_addc_u32 s7, s7, 0
	s_mov_b32 m0, s30
	v_lshl_add_u64 v[248:249], s[6:7], 0, v[134:135]
	ds_read_b128 v[188:191], v153 offset:32768
	ds_read_b128 v[212:215], v153 offset:33792
	ds_read_b128 v[216:219], v153 offset:34816
	ds_read_b128 v[220:223], v153 offset:35840
	ds_read_b128 v[224:227], v153 offset:36864
	ds_read_b128 v[228:231], v153 offset:37888
	ds_read_b128 v[232:235], v153 offset:38912
	ds_read_b128 v[236:239], v153 offset:39936
	global_load_lds_dwordx4 v[248:249], off
	v_lshl_add_u64 v[248:249], s[6:7], 0, v[132:133]
	s_mov_b32 m0, s31
	s_nop 0
	global_load_lds_dwordx4 v[248:249], off
	s_waitcnt vmcnt(8)
	s_waitcnt lgkmcnt(0)
	s_barrier
	s_waitcnt lgkmcnt(0)
	v_mfma_f32_16x16x32_bf16 v[126:129], v[140:143], v[188:191], v[126:129]
	v_mfma_f32_16x16x32_bf16 v[122:125], v[154:157], v[188:191], v[122:125]
	v_mfma_f32_16x16x32_bf16 v[110:113], v[140:143], v[216:219], v[110:113]
	v_mfma_f32_16x16x32_bf16 v[106:109], v[154:157], v[216:219], v[106:109]
	v_mfma_f32_16x16x32_bf16 v[94:97], v[140:143], v[224:227], v[94:97]
	v_mfma_f32_16x16x32_bf16 v[90:93], v[154:157], v[224:227], v[90:93]
	v_mfma_f32_16x16x32_bf16 v[78:81], v[140:143], v[232:235], v[78:81]
	v_mfma_f32_16x16x32_bf16 v[74:77], v[154:157], v[232:235], v[74:77]
	v_mfma_f32_16x16x32_bf16 v[126:129], v[144:147], v[212:215], v[126:129]
	v_mfma_f32_16x16x32_bf16 v[122:125], v[168:171], v[212:215], v[122:125]
	v_mfma_f32_16x16x32_bf16 v[110:113], v[144:147], v[220:223], v[110:113]
	v_mfma_f32_16x16x32_bf16 v[106:109], v[168:171], v[220:223], v[106:109]
	v_mfma_f32_16x16x32_bf16 v[94:97], v[144:147], v[228:231], v[94:97]
	v_mfma_f32_16x16x32_bf16 v[90:93], v[168:171], v[228:231], v[90:93]
	v_mfma_f32_16x16x32_bf16 v[78:81], v[144:147], v[236:239], v[78:81]
	v_mfma_f32_16x16x32_bf16 v[74:77], v[168:171], v[236:239], v[74:77]
	v_mfma_f32_16x16x32_bf16 v[118:121], v[172:175], v[188:191], v[118:121]
	v_mfma_f32_16x16x32_bf16 v[114:117], v[180:183], v[188:191], v[114:117]
	v_mfma_f32_16x16x32_bf16 v[102:105], v[172:175], v[216:219], v[102:105]
	v_mfma_f32_16x16x32_bf16 v[98:101], v[180:183], v[216:219], v[98:101]
	v_mfma_f32_16x16x32_bf16 v[86:89], v[172:175], v[224:227], v[86:89]
	v_mfma_f32_16x16x32_bf16 v[82:85], v[180:183], v[224:227], v[82:85]
	v_mfma_f32_16x16x32_bf16 v[70:73], v[172:175], v[232:235], v[70:73]
	v_mfma_f32_16x16x32_bf16 v[66:69], v[180:183], v[232:235], v[66:69]
	v_mfma_f32_16x16x32_bf16 v[118:121], v[176:179], v[212:215], v[118:121]
	v_mfma_f32_16x16x32_bf16 v[114:117], v[184:187], v[212:215], v[114:117]
	v_mfma_f32_16x16x32_bf16 v[102:105], v[176:179], v[220:223], v[102:105]
	v_mfma_f32_16x16x32_bf16 v[98:101], v[184:187], v[220:223], v[98:101]
	v_mfma_f32_16x16x32_bf16 v[86:89], v[176:179], v[228:231], v[86:89]
	v_mfma_f32_16x16x32_bf16 v[82:85], v[184:187], v[228:231], v[82:85]
	v_mfma_f32_16x16x32_bf16 v[70:73], v[176:179], v[236:239], v[70:73]
	v_mfma_f32_16x16x32_bf16 v[66:69], v[184:187], v[236:239], v[66:69]
	s_barrier
; __device__ __forceinline__ u32x4 pack8(f32x4 a, f32x4 b) { u32x4 w; w.x = cvt_pk_bf16(a[0], a[1]); w.y = cvt_pk_bf16(a[2], a[3]); w.z = cvt_pk_bf16(b[0], b[1]); w.w = cvt_pk_bf16(b[2], b[3]); return w; }
; __device__ __forceinline__ void unpack8(u32x4 w, f32x4& a, f32x4& b) { a = (f32x4){bf_lo(w.x), bf_hi(w.x), bf_lo(w.y), bf_hi(w.y)}; b = (f32x4){bf_lo(w.z), bf_hi(w.z), bf_lo(w.w), bf_hi(w.w)}; }
; #define PG8_STAGE(bufoff, gbase, voff) do { _Pragma("unroll") for (int _i = 0; _i < 2; ++_i) \
;         __builtin_amdgcn_global_load_lds((const unsigned*)((const char*)(gbase) + (voff)[_i]), (PG8_LAS unsigned*)(lds + (bufoff) + ldsw + _i * 8192), 16, 0, 0); } while (0)
; #define PG8_LDA(dst, b, h) do { _Pragma("unroll") for (int m = 0; m < 4; ++m) _Pragma("unroll") for (int k = 0; k < 2; ++k) dst[m][k] = *(const PG8_LAS bf16x8*)(lds + PG8_SA(b, h) + aoff + m * 2048 + k * 1024); } while (0)
; #define PG8_MMA(ai, bj, At, Bt) do { __builtin_amdgcn_s_setprio(1); _Pragma("unroll") for (int m = 0; m < 4; ++m) _Pragma("unroll") for (int n = 0; n < 2; ++n) _Pragma("unroll") for (int k = 0; k < 2; ++k) \
;         acc[ai][bj][m][n] = __builtin_amdgcn_mfma_f32_16x16x32_bf16(Bt[n][k], At[m][k], acc[ai][bj][m][n], 0, 0, 0); __builtin_amdgcn_s_setprio(0); } while (0)
; #define PG8_WAIT_V(n) asm volatile("s_waitcnt vmcnt(" #n ")" ::: "memory")
;     __device__ __forceinline__ void operator()(const f32x4 (&acc)[2][2][4][2], const Unit& u, int wr, int wc, int fr, int fq) const {
;     ...
;                     } else if (MODE == EP_RESID) {
;                         f32x4 x0, x1; unpack8(*(const u32x4*)(xb + row * ldc + col), x0, x1); x0 = x0 + v0; x1 = x1 + v1;
;                         if (O) { *(f32x4*)((float*)O + row * ldc + col) = x0; *(f32x4*)((float*)O + row * ldc + col + 4) = x1; }
;                         if (ssout) {
;                             *(u32x4*)(xb + row * ldc + col) = pack8(x0, x1);
; template <class Epi, class Sched, bool ALIGN_EPI = false, bool SP2 = false>
; __device__ __forceinline__ void gemm_phase(PG8_LAS unsigned char* lds, const Gemm g, const Sched& S, const Epi& E, int wave_in) {
;     ...
;             PG8_LDA(At, 1, 1); PG8_STAGE(PG8_SB(1, 0), b3, voffB); PG8_STAGE(PG8_SB(1, 1), b3 + hstep, voffB); PG8_STAGE(PG8_SA(1, 0), a3, voffA);
;             PG8_WAIT_V(8); PG8_WAIT_L(0); PG8_BAR; PG8_MMA(1, 0, At, B0); PG8_MMA(1, 1, At, B1); PG8_BAR; PG8_SCHED;
	s_add_i32 s6, s44, s27
	v_lshl_add_u64 v[192:193], v[192:193], 0, s[84:85]
	s_mov_b32 m0, s6
	ds_read_b128 v[188:191], v153 offset:49152
	ds_read_b128 v[212:215], v153 offset:50176
	ds_read_b128 v[216:219], v153 offset:51200
	ds_read_b128 v[220:223], v153 offset:52224
	ds_read_b128 v[224:227], v153 offset:53248
	ds_read_b128 v[228:231], v153 offset:54272
	ds_read_b128 v[232:235], v153 offset:55296
	ds_read_b128 v[236:239], v153 offset:56320
	global_load_lds_dwordx4 v[192:193], off
	v_lshl_add_u64 v[192:193], v[200:201], 0, s[84:85]
	s_add_i32 m0, s6, 0x2000
	s_add_i32 s6, s45, s27
	global_load_lds_dwordx4 v[192:193], off
	v_lshl_add_u64 v[192:193], v[240:241], 0, s[84:85]
	s_mov_b32 m0, s6
	s_nop 0
	global_load_lds_dwordx4 v[192:193], off
	v_lshl_add_u64 v[192:193], v[242:243], 0, s[84:85]
	s_add_i32 m0, s6, 0x2000
	s_nop 0
	global_load_lds_dwordx4 v[192:193], off
	v_lshl_add_u64 v[192:193], v[244:245], 0, s[84:85]
	s_mov_b32 m0, s34
	s_nop 0
	global_load_lds_dwordx4 v[192:193], off
	v_lshl_add_u64 v[192:193], v[246:247], 0, s[84:85]
	s_mov_b32 m0, s35
	s_nop 0
	global_load_lds_dwordx4 v[192:193], off
	s_waitcnt vmcnt(8)
	s_waitcnt lgkmcnt(0)
	s_barrier
	s_waitcnt lgkmcnt(0)
	v_mfma_f32_16x16x32_bf16 v[62:65], v[140:143], v[188:191], v[62:65]
	v_mfma_f32_16x16x32_bf16 v[58:61], v[154:157], v[188:191], v[58:61]
	v_mfma_f32_16x16x32_bf16 v[46:49], v[140:143], v[216:219], v[46:49]
	v_mfma_f32_16x16x32_bf16 v[42:45], v[154:157], v[216:219], v[42:45]
	v_mfma_f32_16x16x32_bf16 v[30:33], v[140:143], v[224:227], v[30:33]
	v_mfma_f32_16x16x32_bf16 v[26:29], v[154:157], v[224:227], v[26:29]
	v_mfma_f32_16x16x32_bf16 v[14:17], v[140:143], v[232:235], v[14:17]
	v_mfma_f32_16x16x32_bf16 v[10:13], v[154:157], v[232:235], v[10:13]
	v_mfma_f32_16x16x32_bf16 v[62:65], v[144:147], v[212:215], v[62:65]
	v_mfma_f32_16x16x32_bf16 v[58:61], v[168:171], v[212:215], v[58:61]
	v_mfma_f32_16x16x32_bf16 v[46:49], v[144:147], v[220:223], v[46:49]
	v_mfma_f32_16x16x32_bf16 v[42:45], v[168:171], v[220:223], v[42:45]
	v_mfma_f32_16x16x32_bf16 v[30:33], v[144:147], v[228:231], v[30:33]
	v_mfma_f32_16x16x32_bf16 v[26:29], v[168:171], v[228:231], v[26:29]
	v_mfma_f32_16x16x32_bf16 v[14:17], v[144:147], v[236:239], v[14:17]
	v_mfma_f32_16x16x32_bf16 v[10:13], v[168:171], v[236:239], v[10:13]
	v_mfma_f32_16x16x32_bf16 v[54:57], v[172:175], v[188:191], v[54:57]
	v_mfma_f32_16x16x32_bf16 v[50:53], v[180:183], v[188:191], v[50:53]
	v_mfma_f32_16x16x32_bf16 v[38:41], v[172:175], v[216:219], v[38:41]
	v_mfma_f32_16x16x32_bf16 v[34:37], v[180:183], v[216:219], v[34:37]
	v_mfma_f32_16x16x32_bf16 v[22:25], v[172:175], v[224:227], v[22:25]
	v_mfma_f32_16x16x32_bf16 v[18:21], v[180:183], v[224:227], v[18:21]
	v_mfma_f32_16x16x32_bf16 v[6:9], v[172:175], v[232:235], v[6:9]
	v_mfma_f32_16x16x32_bf16 v[2:5], v[180:183], v[232:235], v[2:5]
	v_mfma_f32_16x16x32_bf16 v[54:57], v[176:179], v[212:215], v[54:57]
	v_mfma_f32_16x16x32_bf16 v[50:53], v[184:187], v[212:215], v[50:53]
	v_mfma_f32_16x16x32_bf16 v[38:41], v[176:179], v[220:223], v[38:41]
	v_mfma_f32_16x16x32_bf16 v[34:37], v[184:187], v[220:223], v[34:37]
	v_mfma_f32_16x16x32_bf16 v[22:25], v[176:179], v[228:231], v[22:25]
	v_mfma_f32_16x16x32_bf16 v[18:21], v[184:187], v[228:231], v[18:21]
	v_mfma_f32_16x16x32_bf16 v[6:9], v[176:179], v[236:239], v[6:9]
	v_mfma_f32_16x16x32_bf16 v[2:5], v[184:187], v[236:239], v[2:5]
	s_barrier
	s_add_u32 s4, s4, 0x100
	s_addc_u32 s5, s5, 0
	s_add_u32 s24, s24, 0x100
	s_addc_u32 s25, s25, 0
	s_cmp_ge_u32 s43, s36
	s_mov_b32 s6, s43
	s_cbranch_scc0 .LBB0_404
	v_readlane_b32 s98, v253, 60
	v_readlane_b32 s99, v253, 61
	v_lshl_add_u32 v166, s42, 8, v148
	v_lshl_or_b32 v167, s41, 8, v152
	v_lshlrev_b32_e32 v167, 1, v167
	s_nop 1
	v_add_u32_e32 v199, 0, v166
	v_lshl_add_u32 v205, v199, 12, v167
	global_load_dwordx4 v[172:175], v205, s[98:99]
	global_load_dwordx4 v[176:179], v205, s[98:99] offset:256
	v_add_u32_e32 v199, 16, v166
	v_lshl_add_u32 v205, v199, 12, v167
	global_load_dwordx4 v[180:183], v205, s[98:99]
	global_load_dwordx4 v[184:187], v205, s[98:99] offset:256
	v_add_u32_e32 v199, 32, v166
	v_lshl_add_u32 v205, v199, 12, v167
	global_load_dwordx4 v[188:191], v205, s[98:99]
	global_load_dwordx4 v[212:215], v205, s[98:99] offset:256
	v_add_u32_e32 v199, 48, v166
	v_lshl_add_u32 v205, v199, 12, v167
	global_load_dwordx4 v[216:219], v205, s[98:99]
	global_load_dwordx4 v[220:223], v205, s[98:99] offset:256
	v_add_u32_e32 v199, 128, v166
	v_lshl_add_u32 v205, v199, 12, v167
	global_load_dwordx4 v[224:227], v205, s[98:99]
	global_load_dwordx4 v[228:231], v205, s[98:99] offset:256
	v_add_u32_e32 v199, 144, v166
	v_lshl_add_u32 v205, v199, 12, v167
	global_load_dwordx4 v[232:235], v205, s[98:99]
	global_load_dwordx4 v[236:239], v205, s[98:99] offset:256
	v_add_u32_e32 v199, 160, v166
	v_lshl_add_u32 v205, v199, 12, v167
	global_load_dwordx4 v[206:209], v205, s[98:99]
	s_and_b64 vcc, exec, s[16:17]
	s_cbranch_vccz .LBB0_407
	s_barrier
.LBB0_407:
	s_cmp_eq_u32 s100, 1
	s_cbranch_scc1 .Lmg_epilogue
	v_lshl_add_u32 v140, s42, 8, v148
	v_ashrrev_i32_e32 v141, 31, v140
	v_readlane_b32 s4, v253, 60
	v_lshl_or_b32 v142, s41, 8, v152
	v_lshlrev_b64 v[144:145], 12, v[140:141]
	v_readlane_b32 s5, v253, 61
	v_ashrrev_i32_e32 v143, 31, v142
	v_cndmask_b32_e64 v146, 0, 1, s[18:19]
	v_lshl_add_u64 v[144:145], s[4:5], 0, v[144:145]
	v_lshl_add_u64 v[144:145], v[142:143], 1, v[144:145]
	s_nop 0
	v_cmp_ne_u32_e64 s[4:5], 1, v146
	v_lshlrev_b64 v[146:147], 11, v[140:141]
	s_andn2_b64 vcc, exec, s[18:19]
	v_lshl_add_u64 v[146:147], v[146:147], 2, s[2:3]
	s_nop 0
	s_waitcnt vmcnt(12)
	v_lshlrev_b32_e32 v168, 16, v172
	v_and_b32_e32 v169, 0xffff0000, v172
	v_lshlrev_b32_e32 v154, 16, v173
	v_and_b32_e32 v155, 0xffff0000, v173
	v_lshlrev_b32_e32 v170, 16, v174
	v_and_b32_e32 v171, 0xffff0000, v174
	v_lshlrev_b32_e32 v156, 16, v175
	v_and_b32_e32 v157, 0xffff0000, v175
	v_add_u32_e32 v199, 160, v166
	v_lshl_add_u32 v205, v199, 12, v167
	global_load_dwordx4 v[172:175], v205, s[98:99] offset:256
	v_pk_add_f32 v[128:129], v[128:129], v[154:155]
	v_pk_add_f32 v[126:127], v[126:127], v[168:169]
	v_pk_add_f32 v[124:125], v[124:125], v[156:157]
	v_pk_add_f32 v[122:123], v[122:123], v[170:171]
	s_cbranch_vccnz .LBB0_409
	v_lshl_add_u64 v[154:155], v[142:143], 2, v[146:147]
	global_store_dwordx4 v[154:155], v[126:129], off
	global_store_dwordx4 v[154:155], v[122:125], off offset:16
